# GU unit seam without the aligning barrier: the one-barrier stagger of the two wave halves persists across units (the leading half's epilogue overlaps the trailing half's last MFMA block and vice versa
# baseline (speedup 1.0000x reference)
; #define LAS __attribute__((address_space(3)))
; __device__ __forceinline__ float siluf_(float x) { return x * sigmoidf_(x); }
; __device__ __forceinline__ void rows_rstd(LAS unsigned char* sl, int rl0, int fq, float (&rs)[8]) {
;     f32x4 v[8];
; #pragma unroll
;     for (int i = 0; i < 8; ++i) v[i] = *(const LAS f32x4*)(sl + (rl0 + (i >> 2) * 128 + (i & 3) * 16) * 64 + fq * 16);
; #pragma unroll
;     for (int i = 0; i < 8; ++i) { float s = (v[i].x + v[i].y) + (v[i].z + v[i].w); s += __shfl_xor(s, 16); s += __shfl_xor(s, 32); rs[i] = rsqrtf(s * (1.0f / DM) + EPS); }
; }
;     __device__ __forceinline__ void operator()(const f32x4 (&acc)[2][2][4][2], const pg8::Unit& u, int wr, int wc, int fr, int fq) const {
;         const int row0 = u.pm * 256 + wr * 64 + fr, col0 = u.pn * 128 + wc * 32 + 8 * fq;
;         float rs[8]; rows_rstd(sl, wr * 64 + fr, fq, rs);
; #pragma unroll
;         for (int ai = 0; ai < 2; ++ai)
; #pragma unroll
;             for (int m = 0; m < 4; ++m) {
;                 const int row = row0 + ai * 128 + m * 16; const float r = rs[ai * 4 + m];
;                 float h[8];
; #pragma unroll
;                 for (int n = 0; n < 2; ++n)
; #pragma unroll
;                     for (int j = 0; j < 4; ++j) { const float g = acc[ai][0][m][n][j] * r, up = acc[ai][1][m][n][j] * r; h[n * 4 + j] = siluf_(g) * up; }
.LBB0_1650:
	v_xor_b32_e32 v130, 16, v175
	v_xor_b32_e32 v131, 32, v175
	ds_read_b128 v[200:203], v198
	ds_read_b128 v[204:207], v198 offset:1024
	ds_read_b128 v[208:211], v198 offset:2048
	ds_read_b128 v[212:215], v198 offset:3072
	ds_read_b128 v[216:219], v198 offset:8192
	ds_read_b128 v[220:223], v198 offset:9216
	ds_read_b128 v[224:227], v198 offset:10240
	ds_read_b128 v[228:231], v198 offset:11264
	v_lshlrev_b32_e32 v130, 2, v130
	v_lshlrev_b32_e32 v131, 2, v131
	v_mov_b32_e32 v134, 0xbfb8aa3b
	v_mov_b32_e32 v135, 0x3a800000
	v_add_u32_e32 v132, s45, v163
	v_mul_u32_u24_e32 v132, 0x1600, v132
	v_lshl_or_b32 v133, s38, 7, v171
	v_lshl_add_u32 v132, v133, 1, v132
	s_waitcnt lgkmcnt(0)
	v_add_f32_e32 v232, v200, v201
	v_add_f32_e32 v233, v204, v205
	v_add_f32_e32 v234, v208, v209
	v_add_f32_e32 v235, v212, v213
	v_add_f32_e32 v236, v216, v217
	v_add_f32_e32 v237, v220, v221
	v_add_f32_e32 v238, v224, v225
	v_add_f32_e32 v239, v228, v229
	v_add_f32_e32 v240, v202, v203
	v_add_f32_e32 v241, v206, v207
	v_add_f32_e32 v242, v210, v211
	v_add_f32_e32 v243, v214, v215
	v_add_f32_e32 v244, v218, v219
	v_add_f32_e32 v245, v222, v223
	v_add_f32_e32 v246, v226, v227
	v_add_f32_e32 v247, v230, v231
	v_add_f32_e32 v232, v232, v240
	v_add_f32_e32 v233, v233, v241
	v_add_f32_e32 v234, v234, v242
	v_add_f32_e32 v235, v235, v243
	v_add_f32_e32 v236, v236, v244
	v_add_f32_e32 v237, v237, v245
	v_add_f32_e32 v238, v238, v246
	v_add_f32_e32 v239, v239, v247
	ds_bpermute_b32 v240, v130, v232
	ds_bpermute_b32 v241, v130, v233
	ds_bpermute_b32 v242, v130, v234
	ds_bpermute_b32 v243, v130, v235
	ds_bpermute_b32 v244, v130, v236
	ds_bpermute_b32 v245, v130, v237
	ds_bpermute_b32 v246, v130, v238
	ds_bpermute_b32 v247, v130, v239
	s_waitcnt lgkmcnt(0)
	v_add_f32_e32 v232, v232, v240
	v_add_f32_e32 v233, v233, v241
	v_add_f32_e32 v234, v234, v242
	v_add_f32_e32 v235, v235, v243
	v_add_f32_e32 v236, v236, v244
	v_add_f32_e32 v237, v237, v245
	v_add_f32_e32 v238, v238, v246
	v_add_f32_e32 v239, v239, v247
	ds_bpermute_b32 v240, v131, v232
	ds_bpermute_b32 v241, v131, v233
	ds_bpermute_b32 v242, v131, v234
	ds_bpermute_b32 v243, v131, v235
	ds_bpermute_b32 v244, v131, v236
	ds_bpermute_b32 v245, v131, v237
	ds_bpermute_b32 v246, v131, v238
	ds_bpermute_b32 v247, v131, v239
	s_waitcnt lgkmcnt(0)
	v_add_f32_e32 v232, v232, v240
	v_add_f32_e32 v233, v233, v241
	v_add_f32_e32 v234, v234, v242
	v_add_f32_e32 v235, v235, v243
	v_add_f32_e32 v236, v236, v244
	v_add_f32_e32 v237, v237, v245
	v_add_f32_e32 v238, v238, v246
	v_add_f32_e32 v239, v239, v247
	v_fmaak_f32 v216, v135, v232, 0x358637bd
	v_fmaak_f32 v218, v135, v233, 0x358637bd
	v_fmaak_f32 v220, v135, v234, 0x358637bd
	v_fmaak_f32 v222, v135, v235, 0x358637bd
	v_fmaak_f32 v224, v135, v236, 0x358637bd
	v_fmaak_f32 v226, v135, v237, 0x358637bd
	v_fmaak_f32 v228, v135, v238, 0x358637bd
	v_fmaak_f32 v230, v135, v239, 0x358637bd
	v_rsq_f32_e32 v200, v216
	v_rsq_f32_e32 v202, v218
	v_rsq_f32_e32 v204, v220
	v_rsq_f32_e32 v206, v222
	v_rsq_f32_e32 v208, v224
	v_rsq_f32_e32 v210, v226
	v_rsq_f32_e32 v212, v228
	v_rsq_f32_e32 v214, v230
	v_mul_f32_e32 v200, v134, v200
	v_mul_f32_e32 v202, v134, v202
	v_mul_f32_e32 v204, v134, v204
	v_mul_f32_e32 v206, v134, v206
	v_mul_f32_e32 v208, v134, v208
	v_mul_f32_e32 v210, v134, v210
	v_mul_f32_e32 v212, v134, v212
	v_mul_f32_e32 v214, v134, v214
	s_andn2_b64 vcc, s[42:43], s[36:37]
	s_cbranch_vccz .LBB0_1652
	s_barrier
.LBB0_1652:
	v_pk_mul_f32 v[120:121], v[124:125], v[120:121]
	v_pk_mul_f32 v[122:123], v[126:127], v[122:123]
	v_pk_mul_f32 v[112:113], v[116:117], v[112:113]
	v_pk_mul_f32 v[114:115], v[118:119], v[114:115]
	v_pk_mul_f32 v[104:105], v[108:109], v[104:105]
	v_pk_mul_f32 v[106:107], v[110:111], v[106:107]
	v_pk_mul_f32 v[96:97], v[100:101], v[96:97]
	v_pk_mul_f32 v[98:99], v[102:103], v[98:99]
	v_pk_mul_f32 v[124:125], v[124:125], v[200:201] op_sel_hi:[1,0]
	v_pk_mul_f32 v[126:127], v[126:127], v[200:201] op_sel_hi:[1,0]
	v_pk_mul_f32 v[116:117], v[116:117], v[200:201] op_sel_hi:[1,0]
	v_pk_mul_f32 v[118:119], v[118:119], v[200:201] op_sel_hi:[1,0]
	v_pk_mul_f32 v[108:109], v[108:109], v[202:203] op_sel_hi:[1,0]
	v_pk_mul_f32 v[110:111], v[110:111], v[202:203] op_sel_hi:[1,0]
	v_pk_mul_f32 v[100:101], v[100:101], v[202:203] op_sel_hi:[1,0]
	v_pk_mul_f32 v[102:103], v[102:103], v[202:203] op_sel_hi:[1,0]
	v_exp_f32_e32 v124, v124
	v_exp_f32_e32 v125, v125
	v_exp_f32_e32 v126, v126
	v_exp_f32_e32 v127, v127
	v_exp_f32_e32 v116, v116
	v_exp_f32_e32 v117, v117
	v_exp_f32_e32 v118, v118
	v_exp_f32_e32 v119, v119
	v_exp_f32_e32 v108, v108
	v_exp_f32_e32 v109, v109
	v_exp_f32_e32 v110, v110
	v_exp_f32_e32 v111, v111
	v_exp_f32_e32 v100, v100
	v_exp_f32_e32 v101, v101
	v_exp_f32_e32 v102, v102
	v_exp_f32_e32 v103, v103
	v_pk_fma_f32 v[124:125], v[124:125], v[216:217], v[216:217] op_sel_hi:[1,0,0]
	v_pk_fma_f32 v[126:127], v[126:127], v[216:217], v[216:217] op_sel_hi:[1,0,0]
	v_pk_fma_f32 v[116:117], v[116:117], v[216:217], v[216:217] op_sel_hi:[1,0,0]
	v_pk_fma_f32 v[118:119], v[118:119], v[216:217], v[216:217] op_sel_hi:[1,0,0]
	v_pk_fma_f32 v[108:109], v[108:109], v[218:219], v[218:219] op_sel_hi:[1,0,0]
	v_pk_fma_f32 v[110:111], v[110:111], v[218:219], v[218:219] op_sel_hi:[1,0,0]
	v_pk_fma_f32 v[100:101], v[100:101], v[218:219], v[218:219] op_sel_hi:[1,0,0]
	v_pk_fma_f32 v[102:103], v[102:103], v[218:219], v[218:219] op_sel_hi:[1,0,0]
	v_rcp_f32_e32 v124, v124
	v_rcp_f32_e32 v125, v125
	v_rcp_f32_e32 v126, v126
	v_rcp_f32_e32 v127, v127
	v_rcp_f32_e32 v116, v116
	v_rcp_f32_e32 v117, v117
	v_rcp_f32_e32 v118, v118
	v_rcp_f32_e32 v119, v119
	v_rcp_f32_e32 v108, v108
; __device__ __forceinline__ unsigned pk2(float lo, float hi) { return pg8::cvt_pk_bf16(lo, hi); }
; __device__ __forceinline__ float siluf_(float x) { return x * sigmoidf_(x); }
;     __device__ __forceinline__ void operator()(const f32x4 (&acc)[2][2][4][2], const pg8::Unit& u, int wr, int wc, int fr, int fq) const {
;     ...
;         for (int ai = 0; ai < 2; ++ai)
; #pragma unroll
;             for (int m = 0; m < 4; ++m) {
;                 const int row = row0 + ai * 128 + m * 16; const float r = rs[ai * 4 + m];
;                 float h[8];
; #pragma unroll
;                 for (int n = 0; n < 2; ++n)
; #pragma unroll
;                     for (int j = 0; j < 4; ++j) { const float g = acc[ai][0][m][n][j] * r, up = acc[ai][1][m][n][j] * r; h[n * 4 + j] = siluf_(g) * up; }
;                 u32x4 w; w.x = pk2(h[0], h[1]); w.y = pk2(h[2], h[3]); w.z = pk2(h[4], h[5]); w.w = pk2(h[6], h[7]);
;                 *(u32x4*)(H + (size_t)row * FF + col0) = w;
;             }
	v_rcp_f32_e32 v109, v109
	v_rcp_f32_e32 v110, v110
	v_rcp_f32_e32 v111, v111
	v_rcp_f32_e32 v100, v100
	v_rcp_f32_e32 v101, v101
	v_rcp_f32_e32 v102, v102
	v_rcp_f32_e32 v103, v103
	v_pk_mul_f32 v[120:121], v[120:121], v[124:125]
	v_pk_mul_f32 v[122:123], v[122:123], v[126:127]
	v_pk_mul_f32 v[112:113], v[112:113], v[116:117]
	v_pk_mul_f32 v[114:115], v[114:115], v[118:119]
	v_pk_mul_f32 v[104:105], v[104:105], v[108:109]
	v_pk_mul_f32 v[106:107], v[106:107], v[110:111]
	v_pk_mul_f32 v[96:97], v[96:97], v[100:101]
	v_pk_mul_f32 v[98:99], v[98:99], v[102:103]
	v_cvt_pk_bf16_f32 v124, v120, v121
	v_cvt_pk_bf16_f32 v125, v122, v123
	v_cvt_pk_bf16_f32 v126, v112, v113
	v_cvt_pk_bf16_f32 v127, v114, v115
	v_cvt_pk_bf16_f32 v108, v104, v105
	v_cvt_pk_bf16_f32 v109, v106, v107
	v_cvt_pk_bf16_f32 v110, v96, v97
	v_cvt_pk_bf16_f32 v111, v98, v99
	v_mov_b32_e32 v136, v132
	global_store_dwordx4 v136, v[124:127], s[8:9] sc1
	v_add_u32_e32 v137, 0x16000, v132
	global_store_dwordx4 v137, v[108:111], s[8:9] sc1
	v_pk_mul_f32 v[88:89], v[92:93], v[88:89]
	v_pk_mul_f32 v[90:91], v[94:95], v[90:91]
	v_pk_mul_f32 v[80:81], v[84:85], v[80:81]
	v_pk_mul_f32 v[82:83], v[86:87], v[82:83]
	v_pk_mul_f32 v[72:73], v[76:77], v[72:73]
	v_pk_mul_f32 v[74:75], v[78:79], v[74:75]
	v_pk_mul_f32 v[64:65], v[68:69], v[64:65]
	v_pk_mul_f32 v[66:67], v[70:71], v[66:67]
	v_pk_mul_f32 v[92:93], v[92:93], v[204:205] op_sel_hi:[1,0]
	v_pk_mul_f32 v[94:95], v[94:95], v[204:205] op_sel_hi:[1,0]
	v_pk_mul_f32 v[84:85], v[84:85], v[204:205] op_sel_hi:[1,0]
	v_pk_mul_f32 v[86:87], v[86:87], v[204:205] op_sel_hi:[1,0]
	v_pk_mul_f32 v[76:77], v[76:77], v[206:207] op_sel_hi:[1,0]
	v_pk_mul_f32 v[78:79], v[78:79], v[206:207] op_sel_hi:[1,0]
	v_pk_mul_f32 v[68:69], v[68:69], v[206:207] op_sel_hi:[1,0]
	v_pk_mul_f32 v[70:71], v[70:71], v[206:207] op_sel_hi:[1,0]
	v_exp_f32_e32 v92, v92
	v_exp_f32_e32 v93, v93
	v_exp_f32_e32 v94, v94
	v_exp_f32_e32 v95, v95
	v_exp_f32_e32 v84, v84
	v_exp_f32_e32 v85, v85
	v_exp_f32_e32 v86, v86
	v_exp_f32_e32 v87, v87
	v_exp_f32_e32 v76, v76
	v_exp_f32_e32 v77, v77
	v_exp_f32_e32 v78, v78
	v_exp_f32_e32 v79, v79
	v_exp_f32_e32 v68, v68
	v_exp_f32_e32 v69, v69
	v_exp_f32_e32 v70, v70
	v_exp_f32_e32 v71, v71
	v_pk_fma_f32 v[92:93], v[92:93], v[220:221], v[220:221] op_sel_hi:[1,0,0]
	v_pk_fma_f32 v[94:95], v[94:95], v[220:221], v[220:221] op_sel_hi:[1,0,0]
	v_pk_fma_f32 v[84:85], v[84:85], v[220:221], v[220:221] op_sel_hi:[1,0,0]
	v_pk_fma_f32 v[86:87], v[86:87], v[220:221], v[220:221] op_sel_hi:[1,0,0]
	v_pk_fma_f32 v[76:77], v[76:77], v[222:223], v[222:223] op_sel_hi:[1,0,0]
	v_pk_fma_f32 v[78:79], v[78:79], v[222:223], v[222:223] op_sel_hi:[1,0,0]
	v_pk_fma_f32 v[68:69], v[68:69], v[222:223], v[222:223] op_sel_hi:[1,0,0]
	v_pk_fma_f32 v[70:71], v[70:71], v[222:223], v[222:223] op_sel_hi:[1,0,0]
	v_rcp_f32_e32 v92, v92
	v_rcp_f32_e32 v93, v93
	v_rcp_f32_e32 v94, v94
	v_rcp_f32_e32 v95, v95
	v_rcp_f32_e32 v84, v84
	v_rcp_f32_e32 v85, v85
	v_rcp_f32_e32 v86, v86
	v_rcp_f32_e32 v87, v87
	v_rcp_f32_e32 v76, v76
	v_rcp_f32_e32 v77, v77
	v_rcp_f32_e32 v78, v78
	v_rcp_f32_e32 v79, v79
	v_rcp_f32_e32 v68, v68
	v_rcp_f32_e32 v69, v69
	v_rcp_f32_e32 v70, v70
	v_rcp_f32_e32 v71, v71
	v_pk_mul_f32 v[88:89], v[88:89], v[92:93]
	v_pk_mul_f32 v[90:91], v[90:91], v[94:95]
	v_pk_mul_f32 v[80:81], v[80:81], v[84:85]
	v_pk_mul_f32 v[82:83], v[82:83], v[86:87]
	v_pk_mul_f32 v[72:73], v[72:73], v[76:77]
	v_pk_mul_f32 v[74:75], v[74:75], v[78:79]
	v_pk_mul_f32 v[64:65], v[64:65], v[68:69]
	v_pk_mul_f32 v[66:67], v[66:67], v[70:71]
	v_cvt_pk_bf16_f32 v92, v88, v89
	v_cvt_pk_bf16_f32 v93, v90, v91
	v_cvt_pk_bf16_f32 v94, v80, v81
	v_cvt_pk_bf16_f32 v95, v82, v83
	v_cvt_pk_bf16_f32 v76, v72, v73
	v_cvt_pk_bf16_f32 v77, v74, v75
	v_cvt_pk_bf16_f32 v78, v64, v65
	v_cvt_pk_bf16_f32 v79, v66, v67
	v_add_u32_e32 v138, 0x2c000, v132
	global_store_dwordx4 v138, v[92:95], s[8:9] sc1
	v_add_u32_e32 v139, 0x42000, v132
	global_store_dwordx4 v139, v[76:79], s[8:9] sc1
	v_pk_mul_f32 v[56:57], v[60:61], v[56:57]
	v_pk_mul_f32 v[58:59], v[62:63], v[58:59]
	v_pk_mul_f32 v[48:49], v[52:53], v[48:49]
	v_pk_mul_f32 v[50:51], v[54:55], v[50:51]
	v_pk_mul_f32 v[40:41], v[44:45], v[40:41]
	v_pk_mul_f32 v[42:43], v[46:47], v[42:43]
	v_pk_mul_f32 v[32:33], v[36:37], v[32:33]
	v_pk_mul_f32 v[34:35], v[38:39], v[34:35]
	v_pk_mul_f32 v[60:61], v[60:61], v[208:209] op_sel_hi:[1,0]
	v_pk_mul_f32 v[62:63], v[62:63], v[208:209] op_sel_hi:[1,0]
	v_pk_mul_f32 v[52:53], v[52:53], v[208:209] op_sel_hi:[1,0]
	v_pk_mul_f32 v[54:55], v[54:55], v[208:209] op_sel_hi:[1,0]
	v_pk_mul_f32 v[44:45], v[44:45], v[210:211] op_sel_hi:[1,0]
	v_pk_mul_f32 v[46:47], v[46:47], v[210:211] op_sel_hi:[1,0]
	v_pk_mul_f32 v[36:37], v[36:37], v[210:211] op_sel_hi:[1,0]
	v_pk_mul_f32 v[38:39], v[38:39], v[210:211] op_sel_hi:[1,0]
	v_exp_f32_e32 v60, v60
	v_exp_f32_e32 v61, v61
	v_exp_f32_e32 v62, v62
	v_exp_f32_e32 v63, v63
	v_exp_f32_e32 v52, v52
	v_exp_f32_e32 v53, v53
	v_exp_f32_e32 v54, v54
	v_exp_f32_e32 v55, v55
; #define PG8_BAR __builtin_amdgcn_s_barrier()
; __device__ __forceinline__ unsigned pk2(float lo, float hi) { return pg8::cvt_pk_bf16(lo, hi); }
; __device__ __forceinline__ float siluf_(float x) { return x * sigmoidf_(x); }
; template <class Epi, class Sched, bool ALIGN_EPI = false, bool SP2 = false>
; __device__ __forceinline__ void gemm_phase(PG8_LAS unsigned char* lds, const Gemm g, const Sched& S, const Epi& E) {
;     ...
;         if constexpr (ALIGN_EPI) { if (wr == 0) PG8_BAR; }
;         if constexpr (!Epi::AFTER_DRAIN) { E(acc, cur, wr, wc, fr, fq); S.done(cur); }
;         if (!has_next) break;
;         { typename Epi::Pre pren = E.issue(nxt, wr, wc, fr, fq); E.finish(acc, pren); }
;         cur = nxt; cA = nA; cB = nB; ++ui;
;         if constexpr (ALIGN_EPI) { if (wr == 1) PG8_BAR; }
;     __device__ __forceinline__ void operator()(const f32x4 (&acc)[2][2][4][2], const pg8::Unit& u, int wr, int wc, int fr, int fq) const {
;     ...
;         for (int ai = 0; ai < 2; ++ai)
; #pragma unroll
;             for (int m = 0; m < 4; ++m) {
;                 const int row = row0 + ai * 128 + m * 16; const float r = rs[ai * 4 + m];
;                 float h[8];
; #pragma unroll
;                 for (int n = 0; n < 2; ++n)
; #pragma unroll
;                     for (int j = 0; j < 4; ++j) { const float g = acc[ai][0][m][n][j] * r, up = acc[ai][1][m][n][j] * r; h[n * 4 + j] = siluf_(g) * up; }
;                 u32x4 w; w.x = pk2(h[0], h[1]); w.y = pk2(h[2], h[3]); w.z = pk2(h[4], h[5]); w.w = pk2(h[6], h[7]);
;                 *(u32x4*)(H + (size_t)row * FF + col0) = w;
;             }
	v_exp_f32_e32 v44, v44
	v_exp_f32_e32 v45, v45
	v_exp_f32_e32 v46, v46
	v_exp_f32_e32 v47, v47
	v_exp_f32_e32 v36, v36
	v_exp_f32_e32 v37, v37
	v_exp_f32_e32 v38, v38
	v_exp_f32_e32 v39, v39
	v_pk_fma_f32 v[60:61], v[60:61], v[224:225], v[224:225] op_sel_hi:[1,0,0]
	v_pk_fma_f32 v[62:63], v[62:63], v[224:225], v[224:225] op_sel_hi:[1,0,0]
	v_pk_fma_f32 v[52:53], v[52:53], v[224:225], v[224:225] op_sel_hi:[1,0,0]
	v_pk_fma_f32 v[54:55], v[54:55], v[224:225], v[224:225] op_sel_hi:[1,0,0]
	v_pk_fma_f32 v[44:45], v[44:45], v[226:227], v[226:227] op_sel_hi:[1,0,0]
	v_pk_fma_f32 v[46:47], v[46:47], v[226:227], v[226:227] op_sel_hi:[1,0,0]
	v_pk_fma_f32 v[36:37], v[36:37], v[226:227], v[226:227] op_sel_hi:[1,0,0]
	v_pk_fma_f32 v[38:39], v[38:39], v[226:227], v[226:227] op_sel_hi:[1,0,0]
	v_rcp_f32_e32 v60, v60
	v_rcp_f32_e32 v61, v61
	v_rcp_f32_e32 v62, v62
	v_rcp_f32_e32 v63, v63
	v_rcp_f32_e32 v52, v52
	v_rcp_f32_e32 v53, v53
	v_rcp_f32_e32 v54, v54
	v_rcp_f32_e32 v55, v55
	v_rcp_f32_e32 v44, v44
	v_rcp_f32_e32 v45, v45
	v_rcp_f32_e32 v46, v46
	v_rcp_f32_e32 v47, v47
	v_rcp_f32_e32 v36, v36
	v_rcp_f32_e32 v37, v37
	v_rcp_f32_e32 v38, v38
	v_rcp_f32_e32 v39, v39
	v_pk_mul_f32 v[56:57], v[56:57], v[60:61]
	v_pk_mul_f32 v[58:59], v[58:59], v[62:63]
	v_pk_mul_f32 v[48:49], v[48:49], v[52:53]
	v_pk_mul_f32 v[50:51], v[50:51], v[54:55]
	v_pk_mul_f32 v[40:41], v[40:41], v[44:45]
	v_pk_mul_f32 v[42:43], v[42:43], v[46:47]
	v_pk_mul_f32 v[32:33], v[32:33], v[36:37]
	v_pk_mul_f32 v[34:35], v[34:35], v[38:39]
	v_cvt_pk_bf16_f32 v60, v56, v57
	v_cvt_pk_bf16_f32 v61, v58, v59
	v_cvt_pk_bf16_f32 v62, v48, v49
	v_cvt_pk_bf16_f32 v63, v50, v51
	v_cvt_pk_bf16_f32 v44, v40, v41
	v_cvt_pk_bf16_f32 v45, v42, v43
	v_cvt_pk_bf16_f32 v46, v32, v33
	v_cvt_pk_bf16_f32 v47, v34, v35
	v_add_u32_e32 v140, 0xb0000, v132
	global_store_dwordx4 v140, v[60:63], s[8:9] sc1
	v_add_u32_e32 v141, 0xc6000, v132
	global_store_dwordx4 v141, v[44:47], s[8:9] sc1
	v_pk_mul_f32 v[24:25], v[28:29], v[24:25]
	v_pk_mul_f32 v[26:27], v[30:31], v[26:27]
	v_pk_mul_f32 v[16:17], v[20:21], v[16:17]
	v_pk_mul_f32 v[18:19], v[22:23], v[18:19]
	v_pk_mul_f32 v[8:9], v[12:13], v[8:9]
	v_pk_mul_f32 v[10:11], v[14:15], v[10:11]
	v_pk_mul_f32 v[0:1], v[4:5], v[0:1]
	v_pk_mul_f32 v[2:3], v[6:7], v[2:3]
	v_pk_mul_f32 v[28:29], v[28:29], v[212:213] op_sel_hi:[1,0]
	v_pk_mul_f32 v[30:31], v[30:31], v[212:213] op_sel_hi:[1,0]
	v_pk_mul_f32 v[20:21], v[20:21], v[212:213] op_sel_hi:[1,0]
	v_pk_mul_f32 v[22:23], v[22:23], v[212:213] op_sel_hi:[1,0]
	v_pk_mul_f32 v[12:13], v[12:13], v[214:215] op_sel_hi:[1,0]
	v_pk_mul_f32 v[14:15], v[14:15], v[214:215] op_sel_hi:[1,0]
	v_pk_mul_f32 v[4:5], v[4:5], v[214:215] op_sel_hi:[1,0]
	v_pk_mul_f32 v[6:7], v[6:7], v[214:215] op_sel_hi:[1,0]
	v_exp_f32_e32 v28, v28
	v_exp_f32_e32 v29, v29
	v_exp_f32_e32 v30, v30
	v_exp_f32_e32 v31, v31
	v_exp_f32_e32 v20, v20
	v_exp_f32_e32 v21, v21
	v_exp_f32_e32 v22, v22
	v_exp_f32_e32 v23, v23
	v_exp_f32_e32 v12, v12
	v_exp_f32_e32 v13, v13
	v_exp_f32_e32 v14, v14
	v_exp_f32_e32 v15, v15
	v_exp_f32_e32 v4, v4
	v_exp_f32_e32 v5, v5
	v_exp_f32_e32 v6, v6
	v_exp_f32_e32 v7, v7
	v_pk_fma_f32 v[28:29], v[28:29], v[228:229], v[228:229] op_sel_hi:[1,0,0]
	v_pk_fma_f32 v[30:31], v[30:31], v[228:229], v[228:229] op_sel_hi:[1,0,0]
	v_pk_fma_f32 v[20:21], v[20:21], v[228:229], v[228:229] op_sel_hi:[1,0,0]
	v_pk_fma_f32 v[22:23], v[22:23], v[228:229], v[228:229] op_sel_hi:[1,0,0]
	v_pk_fma_f32 v[12:13], v[12:13], v[230:231], v[230:231] op_sel_hi:[1,0,0]
	v_pk_fma_f32 v[14:15], v[14:15], v[230:231], v[230:231] op_sel_hi:[1,0,0]
	v_pk_fma_f32 v[4:5], v[4:5], v[230:231], v[230:231] op_sel_hi:[1,0,0]
	v_pk_fma_f32 v[6:7], v[6:7], v[230:231], v[230:231] op_sel_hi:[1,0,0]
	v_rcp_f32_e32 v28, v28
	v_rcp_f32_e32 v29, v29
	v_rcp_f32_e32 v30, v30
	v_rcp_f32_e32 v31, v31
	v_rcp_f32_e32 v20, v20
	v_rcp_f32_e32 v21, v21
	v_rcp_f32_e32 v22, v22
	v_rcp_f32_e32 v23, v23
	v_rcp_f32_e32 v12, v12
	v_rcp_f32_e32 v13, v13
	v_rcp_f32_e32 v14, v14
	v_rcp_f32_e32 v15, v15
	v_rcp_f32_e32 v4, v4
	v_rcp_f32_e32 v5, v5
	v_rcp_f32_e32 v6, v6
	v_rcp_f32_e32 v7, v7
	v_pk_mul_f32 v[24:25], v[24:25], v[28:29]
	v_pk_mul_f32 v[26:27], v[26:27], v[30:31]
	v_pk_mul_f32 v[16:17], v[16:17], v[20:21]
	v_pk_mul_f32 v[18:19], v[18:19], v[22:23]
	v_pk_mul_f32 v[8:9], v[8:9], v[12:13]
	v_pk_mul_f32 v[10:11], v[10:11], v[14:15]
	v_pk_mul_f32 v[0:1], v[0:1], v[4:5]
	v_pk_mul_f32 v[2:3], v[2:3], v[6:7]
	v_cvt_pk_bf16_f32 v28, v24, v25
	v_cvt_pk_bf16_f32 v29, v26, v27
	v_cvt_pk_bf16_f32 v30, v16, v17
	v_cvt_pk_bf16_f32 v31, v18, v19
	v_cvt_pk_bf16_f32 v12, v8, v9
	v_cvt_pk_bf16_f32 v13, v10, v11
	v_cvt_pk_bf16_f32 v14, v0, v1
	v_cvt_pk_bf16_f32 v15, v2, v3
	v_add_u32_e32 v142, 0xdc000, v132
	global_store_dwordx4 v142, v[28:31], s[8:9] sc1
	v_add_u32_e32 v143, 0xf2000, v132
	global_store_dwordx4 v143, v[12:15], s[8:9] sc1
	s_andn2_b64 vcc, exec, s[36:37]
	s_mov_b64 s[0:1], -1
	s_cbranch_vccnz .LBB0_1643
	s_andn2_b64 vcc, exec, s[40:41]
	s_cbranch_vccnz .LBB0_1642
	s_branch .LBB0_1642
